# attention loop: uniform VALU density (next-tile exps pipelined into PV slots), tail copy for last half
# speedup vs baseline: 1.0138x; 1.0138x over previous
.LBB0_206:
	s_mov_b32 s99, 0
	v_mov_b64_e32 v[158:159], v[134:135]
	v_mov_b64_e32 v[160:161], v[132:133]
	ds_read_b128 v[222:225], v186 offset:9216
	ds_read_b128 v[226:229], v186 offset:13824
	ds_read_b128 v[230:233], v186 offset:9248
	ds_read_b128 v[234:237], v186 offset:13856
	ds_read_b128 v[138:141], v186 offset:9280
	ds_read_b128 v[142:145], v186 offset:13888
	ds_read_b128 v[162:165], v186 offset:9312
	ds_read_b128 v[132:135], v186 offset:13920
	v_exp_f32_e32 v32, v32
	v_exp_f32_e32 v33, v33
	v_exp_f32_e32 v34, v34
	v_exp_f32_e32 v35, v35
	v_exp_f32_e32 v36, v36
	v_exp_f32_e32 v37, v37
	v_exp_f32_e32 v38, v38
	v_exp_f32_e32 v39, v39
	v_exp_f32_e32 v40, v40
	v_exp_f32_e32 v41, v41
	v_exp_f32_e32 v42, v42
	v_exp_f32_e32 v43, v43
	v_exp_f32_e32 v44, v44
	v_exp_f32_e32 v45, v45
	v_exp_f32_e32 v46, v46
	v_exp_f32_e32 v47, v47
.Lattn_main:
	s_mov_b32 s84, s7
	s_waitcnt lgkmcnt(7)
	v_mfma_f32_32x32x16_bf16 v[64:79], v[222:225], v[96:99], 0
	ds_read_b128 v[222:225], v186 offset:36864
	v_add_f32_e32 v188, v188, v32
	v_add_f32_e32 v189, v189, v33
	v_cvt_pk_bf16_f32 v32, v32, v33
	v_add_f32_e32 v190, v190, v34
	v_add_f32_e32 v191, v191, v35
	v_cvt_pk_bf16_f32 v33, v34, v35
	v_exp_f32_e32 v48, v48
	v_exp_f32_e32 v49, v49
	s_waitcnt lgkmcnt(7)
	v_mfma_f32_32x32x16_bf16 v[206:221], v[226:229], v[96:99], 0
	ds_read_b128 v[226:229], v186 offset:41472
	v_add_f32_e32 v192, v192, v36
	v_add_f32_e32 v193, v193, v37
	v_cvt_pk_bf16_f32 v34, v36, v37
	v_exp_f32_e32 v50, v50
	v_exp_f32_e32 v51, v51
	s_waitcnt lgkmcnt(7)
	v_mfma_f32_32x32x16_bf16 v[64:79], v[230:233], v[100:103], v[64:79]
	ds_read_b128 v[230:233], v186 offset:36896
	v_add_f32_e32 v194, v194, v38
	v_add_f32_e32 v195, v195, v39
	v_cvt_pk_bf16_f32 v35, v38, v39
	v_exp_f32_e32 v52, v52
	v_exp_f32_e32 v53, v53
	s_waitcnt lgkmcnt(7)
	v_mfma_f32_32x32x16_bf16 v[206:221], v[234:237], v[100:103], v[206:221]
	ds_read_b128 v[234:237], v186 offset:41504
	v_add_f32_e32 v196, v196, v40
	v_add_f32_e32 v197, v197, v41
	v_cvt_pk_bf16_f32 v36, v40, v41
	v_exp_f32_e32 v54, v54
	v_exp_f32_e32 v55, v55
	s_waitcnt lgkmcnt(7)
	v_mfma_f32_32x32x16_bf16 v[64:79], v[138:141], v[104:107], v[64:79]
	ds_read_b128 v[138:141], v186 offset:36928
	v_add_f32_e32 v198, v198, v42
	v_add_f32_e32 v199, v199, v43
	v_cvt_pk_bf16_f32 v37, v42, v43
	v_exp_f32_e32 v56, v56
	v_exp_f32_e32 v57, v57
	s_waitcnt lgkmcnt(7)
	v_mfma_f32_32x32x16_bf16 v[206:221], v[142:145], v[104:107], v[206:221]
	ds_read_b128 v[142:145], v186 offset:41536
	v_add_f32_e32 v200, v200, v44
	v_add_f32_e32 v201, v201, v45
	v_cvt_pk_bf16_f32 v38, v44, v45
	v_exp_f32_e32 v58, v58
	v_exp_f32_e32 v59, v59
	s_waitcnt lgkmcnt(7)
	v_mfma_f32_32x32x16_bf16 v[64:79], v[162:165], v[108:111], v[64:79]
	ds_read_b128 v[162:165], v186 offset:36960
	v_add_f32_e32 v202, v202, v46
	v_add_f32_e32 v203, v203, v47
	v_cvt_pk_bf16_f32 v39, v46, v47
	v_exp_f32_e32 v60, v60
	v_exp_f32_e32 v61, v61
	s_waitcnt lgkmcnt(7)
	v_mfma_f32_32x32x16_bf16 v[206:221], v[132:135], v[108:111], v[206:221]
	ds_read_b128 v[132:135], v186 offset:41568
	v_add_f32_e32 v188, v188, v48
	v_add_f32_e32 v189, v189, v49
	v_cvt_pk_bf16_f32 v48, v48, v49
	v_add_f32_e32 v190, v190, v50
	v_add_f32_e32 v191, v191, v51
	v_cvt_pk_bf16_f32 v49, v50, v51
	v_exp_f32_e32 v62, v62
	v_exp_f32_e32 v63, v63
	s_waitcnt lgkmcnt(7)
	v_mfma_f32_32x32x16_bf16 v[0:15], v[222:225], v[32:35], v[0:15]
	ds_read_b128 v[222:225], v186 offset:18432
	v_add_f32_e32 v192, v192, v52
	v_add_f32_e32 v193, v193, v53
	v_cvt_pk_bf16_f32 v50, v52, v53
	v_exp_f32_e32 v64, v64
	v_exp_f32_e32 v65, v65
	s_waitcnt lgkmcnt(7)
	v_mfma_f32_32x32x16_bf16 v[16:31], v[226:229], v[32:35], v[16:31]
	ds_read_b128 v[226:229], v186 offset:23040
	v_add_f32_e32 v194, v194, v54
	v_add_f32_e32 v195, v195, v55
	v_cvt_pk_bf16_f32 v51, v54, v55
	v_exp_f32_e32 v66, v66
	v_exp_f32_e32 v67, v67
	s_waitcnt lgkmcnt(7)
	v_mfma_f32_32x32x16_bf16 v[0:15], v[230:233], v[36:39], v[0:15]
	ds_read_b128 v[230:233], v186 offset:18464
	v_add_f32_e32 v196, v196, v56
	v_add_f32_e32 v197, v197, v57
	v_cvt_pk_bf16_f32 v52, v56, v57
	v_exp_f32_e32 v68, v68
	v_exp_f32_e32 v69, v69
	v_add_u32_e32 v204, 0xd800, v136
	v_add_u32_e32 v205, 0xf800, v136
	s_waitcnt vmcnt(3)
	ds_write_b128 v168, v[112:115] offset:27648
	s_waitcnt vmcnt(2)
	s_waitcnt lgkmcnt(8)
	v_mfma_f32_32x32x16_bf16 v[16:31], v[234:237], v[36:39], v[16:31]
	ds_read_b128 v[234:237], v186 offset:23072
	v_add_f32_e32 v198, v198, v58
	v_add_f32_e32 v199, v199, v59
	v_cvt_pk_bf16_f32 v53, v58, v59
	v_exp_f32_e32 v70, v70
	v_exp_f32_e32 v71, v71
	ds_write_b128 v168, v[116:119]
	s_waitcnt vmcnt(1)
	ds_write2_b64 v204, v[120:121], v[122:123] offset1:2
	s_waitcnt vmcnt(0)
	ds_write2_b64 v205, v[124:125], v[126:127] offset0:128 offset1:130
	s_waitcnt lgkmcnt(11)
	v_mfma_f32_32x32x16_bf16 v[0:15], v[138:141], v[48:51], v[0:15]
	ds_read_b128 v[138:141], v186 offset:18496
	v_add_f32_e32 v200, v200, v60
	v_add_f32_e32 v201, v201, v61
	v_cvt_pk_bf16_f32 v54, v60, v61
	v_exp_f32_e32 v72, v72
	v_exp_f32_e32 v73, v73
	v_lshl_add_u64 v[120:121], v[128:129], 0, v[150:151]
	v_lshl_add_u64 v[124:125], v[130:131], 0, v[150:151]
	s_mov_b32 s98, 0xd8c8000
	v_lshl_add_u64 v[146:147], v[120:121], 0, s[98:99]
	global_load_dwordx4 v[80:83], v[146:147], off offset:2304
	s_waitcnt lgkmcnt(11)
	v_mfma_f32_32x32x16_bf16 v[16:31], v[142:145], v[48:51], v[16:31]
	ds_read_b128 v[142:145], v186 offset:23104
	v_add_f32_e32 v202, v202, v62
	v_add_f32_e32 v203, v203, v63
	v_cvt_pk_bf16_f32 v55, v62, v63
	v_exp_f32_e32 v74, v74
	v_exp_f32_e32 v75, v75
	s_mov_b32 s98, 0xd8f0000
	v_lshl_add_u64 v[146:147], v[120:121], 0, s[98:99]
	global_load_dwordx4 v[84:87], v[146:147], off offset:2304
	s_mov_b32 s98, 0x17820000
	v_lshl_add_u64 v[146:147], v[124:125], 0, s[98:99]
	s_waitcnt lgkmcnt(11)
	v_mfma_f32_32x32x16_bf16 v[0:15], v[162:165], v[52:55], v[0:15]
	ds_read_b128 v[162:165], v186 offset:18528
	v_exp_f32_e32 v76, v76
	v_exp_f32_e32 v77, v77
	global_load_dwordx4 v[88:91], v[146:147], off
	s_mov_b32 s98, 0x17828000
	v_lshl_add_u64 v[146:147], v[124:125], 0, s[98:99]
	global_load_dwordx4 v[92:95], v[146:147], off
	v_lshl_add_u64 v[128:129], v[128:129], 0, s[26:27]
	s_waitcnt lgkmcnt(11)
	v_mfma_f32_32x32x16_bf16 v[16:31], v[132:135], v[52:55], v[16:31]
	ds_read_b128 v[132:135], v186 offset:23136
	v_exp_f32_e32 v78, v78
	v_exp_f32_e32 v79, v79
	v_lshl_add_u64 v[130:131], v[130:131], 0, s[28:29]
	s_mov_b32 s14, s8
	s_add_i32 s6, s6, 4
	s_add_i32 s8, s8, 4
	s_waitcnt lgkmcnt(11)
	v_mfma_f32_32x32x16_bf16 v[32:47], v[222:225], v[96:99], 0
	ds_read_b128 v[222:225], v186 offset:46080
	v_add_f32_e32 v188, v188, v64
	v_add_f32_e32 v189, v189, v65
	v_cvt_pk_bf16_f32 v64, v64, v65
	v_add_f32_e32 v190, v190, v66
	v_add_f32_e32 v191, v191, v67
	v_cvt_pk_bf16_f32 v65, v66, v67
	v_exp_f32_e32 v206, v206
	v_exp_f32_e32 v207, v207
	s_waitcnt lgkmcnt(11)
	v_mfma_f32_32x32x16_bf16 v[48:63], v[226:229], v[96:99], 0
	ds_read_b128 v[226:229], v186 offset:50688
	v_add_f32_e32 v192, v192, v68
	v_add_f32_e32 v193, v193, v69
	v_cvt_pk_bf16_f32 v66, v68, v69
	v_exp_f32_e32 v208, v208
	v_exp_f32_e32 v209, v209
	s_waitcnt lgkmcnt(11)
	v_mfma_f32_32x32x16_bf16 v[32:47], v[230:233], v[100:103], v[32:47]
	ds_read_b128 v[230:233], v186 offset:46112
	v_add_f32_e32 v194, v194, v70
	v_add_f32_e32 v195, v195, v71
	v_cvt_pk_bf16_f32 v67, v70, v71
	v_exp_f32_e32 v210, v210
	v_exp_f32_e32 v211, v211
	s_waitcnt lgkmcnt(10)
	v_mfma_f32_32x32x16_bf16 v[48:63], v[234:237], v[100:103], v[48:63]
	ds_read_b128 v[234:237], v186 offset:50720
	v_add_f32_e32 v196, v196, v72
	v_add_f32_e32 v197, v197, v73
	v_cvt_pk_bf16_f32 v68, v72, v73
	v_exp_f32_e32 v212, v212
	v_exp_f32_e32 v213, v213
	s_waitcnt lgkmcnt(7)
	v_mfma_f32_32x32x16_bf16 v[32:47], v[138:141], v[104:107], v[32:47]
	ds_read_b128 v[138:141], v186 offset:46144
	v_add_f32_e32 v198, v198, v74
	v_add_f32_e32 v199, v199, v75
	v_cvt_pk_bf16_f32 v69, v74, v75
	v_exp_f32_e32 v214, v214
	v_exp_f32_e32 v215, v215
	s_waitcnt lgkmcnt(7)
	v_mfma_f32_32x32x16_bf16 v[48:63], v[142:145], v[104:107], v[48:63]
	ds_read_b128 v[142:145], v186 offset:50752
	v_add_f32_e32 v200, v200, v76
	v_add_f32_e32 v201, v201, v77
	v_cvt_pk_bf16_f32 v70, v76, v77
	v_exp_f32_e32 v216, v216
	v_exp_f32_e32 v217, v217
	s_waitcnt lgkmcnt(7)
	v_mfma_f32_32x32x16_bf16 v[32:47], v[162:165], v[108:111], v[32:47]
	ds_read_b128 v[162:165], v186 offset:46176
	v_add_f32_e32 v202, v202, v78
	v_add_f32_e32 v203, v203, v79
	v_cvt_pk_bf16_f32 v71, v78, v79
	v_exp_f32_e32 v218, v218
	v_exp_f32_e32 v219, v219
	s_waitcnt lgkmcnt(7)
	v_mfma_f32_32x32x16_bf16 v[48:63], v[132:135], v[108:111], v[48:63]
	ds_read_b128 v[132:135], v186 offset:50784
	v_add_f32_e32 v188, v188, v206
	v_add_f32_e32 v189, v189, v207
	v_cvt_pk_bf16_f32 v206, v206, v207
	v_add_f32_e32 v190, v190, v208
	v_add_f32_e32 v191, v191, v209
	v_cvt_pk_bf16_f32 v207, v208, v209
	v_exp_f32_e32 v220, v220
	v_exp_f32_e32 v221, v221
	s_waitcnt lgkmcnt(7)
	v_mfma_f32_32x32x16_bf16 v[0:15], v[222:225], v[64:67], v[0:15]
	v_add_f32_e32 v192, v192, v210
	v_add_f32_e32 v193, v193, v211
	v_cvt_pk_bf16_f32 v208, v210, v211
	v_exp_f32_e32 v32, v32
	v_exp_f32_e32 v33, v33
	s_waitcnt lgkmcnt(6)
	v_mfma_f32_32x32x16_bf16 v[16:31], v[226:229], v[64:67], v[16:31]
	v_add_f32_e32 v194, v194, v212
	v_add_f32_e32 v195, v195, v213
	v_cvt_pk_bf16_f32 v209, v212, v213
	v_exp_f32_e32 v34, v34
	v_exp_f32_e32 v35, v35
	s_waitcnt lgkmcnt(5)
	v_mfma_f32_32x32x16_bf16 v[0:15], v[230:233], v[68:71], v[0:15]
	v_add_f32_e32 v196, v196, v214
	v_add_f32_e32 v197, v197, v215
	v_cvt_pk_bf16_f32 v210, v214, v215
	v_exp_f32_e32 v36, v36
	v_exp_f32_e32 v37, v37
	s_waitcnt lgkmcnt(4)
	v_mfma_f32_32x32x16_bf16 v[16:31], v[234:237], v[68:71], v[16:31]
	s_waitcnt lgkmcnt(0)
	s_barrier
	ds_read_b128 v[222:225], v186 offset:27648
	ds_read_b128 v[226:229], v186 offset:32256
	ds_read_b128 v[230:233], v186 offset:27680
	ds_read_b128 v[234:237], v186 offset:32288
	v_add_f32_e32 v198, v198, v216
	v_add_f32_e32 v199, v199, v217
	v_cvt_pk_bf16_f32 v211, v216, v217
	v_exp_f32_e32 v38, v38
	v_exp_f32_e32 v39, v39
	v_mfma_f32_32x32x16_bf16 v[0:15], v[138:141], v[206:209], v[0:15]
	ds_read_b128 v[138:141], v186 offset:27712
	v_add_f32_e32 v200, v200, v218
	v_add_f32_e32 v201, v201, v219
	v_cvt_pk_bf16_f32 v212, v218, v219
	v_exp_f32_e32 v40, v40
	v_exp_f32_e32 v41, v41
	v_mfma_f32_32x32x16_bf16 v[16:31], v[142:145], v[206:209], v[16:31]
	ds_read_b128 v[142:145], v186 offset:32320
	v_add_f32_e32 v202, v202, v220
	v_add_f32_e32 v203, v203, v221
	v_cvt_pk_bf16_f32 v213, v220, v221
	v_exp_f32_e32 v42, v42
	v_exp_f32_e32 v43, v43
	v_mfma_f32_32x32x16_bf16 v[0:15], v[162:165], v[210:213], v[0:15]
	ds_read_b128 v[162:165], v186 offset:27744
	v_exp_f32_e32 v44, v44
	v_exp_f32_e32 v45, v45
	v_mfma_f32_32x32x16_bf16 v[16:31], v[132:135], v[210:213], v[16:31]
	ds_read_b128 v[132:135], v186 offset:32352
	v_exp_f32_e32 v46, v46
	v_exp_f32_e32 v47, v47
	s_waitcnt lgkmcnt(7)
	v_mfma_f32_32x32x16_bf16 v[64:79], v[222:225], v[96:99], 0
	ds_read_b128 v[222:225], v186 offset:55296
	v_add_f32_e32 v188, v188, v32
	v_add_f32_e32 v189, v189, v33
	v_cvt_pk_bf16_f32 v32, v32, v33
	v_add_f32_e32 v190, v190, v34
	v_add_f32_e32 v191, v191, v35
	v_cvt_pk_bf16_f32 v33, v34, v35
	v_exp_f32_e32 v48, v48
	v_exp_f32_e32 v49, v49
	s_waitcnt lgkmcnt(7)
	v_mfma_f32_32x32x16_bf16 v[206:221], v[226:229], v[96:99], 0
	ds_read_b128 v[226:229], v186 offset:59904
	v_add_f32_e32 v192, v192, v36
	v_add_f32_e32 v193, v193, v37
	v_cvt_pk_bf16_f32 v34, v36, v37
	v_exp_f32_e32 v50, v50
	v_exp_f32_e32 v51, v51
	s_waitcnt lgkmcnt(7)
	v_mfma_f32_32x32x16_bf16 v[64:79], v[230:233], v[100:103], v[64:79]
	ds_read_b128 v[230:233], v186 offset:55328
	v_add_f32_e32 v194, v194, v38
	v_add_f32_e32 v195, v195, v39
	v_cvt_pk_bf16_f32 v35, v38, v39
	v_exp_f32_e32 v52, v52
	v_exp_f32_e32 v53, v53
	s_waitcnt lgkmcnt(7)
	v_mfma_f32_32x32x16_bf16 v[206:221], v[234:237], v[100:103], v[206:221]
	ds_read_b128 v[234:237], v186 offset:59936
	v_add_f32_e32 v196, v196, v40
	v_add_f32_e32 v197, v197, v41
	v_cvt_pk_bf16_f32 v36, v40, v41
	v_exp_f32_e32 v54, v54
	v_exp_f32_e32 v55, v55
	s_waitcnt lgkmcnt(7)
	v_mfma_f32_32x32x16_bf16 v[64:79], v[138:141], v[104:107], v[64:79]
	ds_read_b128 v[138:141], v186 offset:55360
	v_add_f32_e32 v198, v198, v42
	v_add_f32_e32 v199, v199, v43
	v_cvt_pk_bf16_f32 v37, v42, v43
	v_exp_f32_e32 v56, v56
	v_exp_f32_e32 v57, v57
	s_waitcnt lgkmcnt(7)
	v_mfma_f32_32x32x16_bf16 v[206:221], v[142:145], v[104:107], v[206:221]
	ds_read_b128 v[142:145], v186 offset:59968
	v_add_f32_e32 v200, v200, v44
	v_add_f32_e32 v201, v201, v45
	v_cvt_pk_bf16_f32 v38, v44, v45
	v_exp_f32_e32 v58, v58
	v_exp_f32_e32 v59, v59
	s_waitcnt lgkmcnt(7)
	v_mfma_f32_32x32x16_bf16 v[64:79], v[162:165], v[108:111], v[64:79]
	ds_read_b128 v[162:165], v186 offset:55392
	v_add_f32_e32 v202, v202, v46
	v_add_f32_e32 v203, v203, v47
	v_cvt_pk_bf16_f32 v39, v46, v47
	v_exp_f32_e32 v60, v60
	v_exp_f32_e32 v61, v61
	s_waitcnt lgkmcnt(7)
	v_mfma_f32_32x32x16_bf16 v[206:221], v[132:135], v[108:111], v[206:221]
	ds_read_b128 v[132:135], v186 offset:60000
	v_add_f32_e32 v188, v188, v48
	v_add_f32_e32 v189, v189, v49
	v_cvt_pk_bf16_f32 v48, v48, v49
	v_add_f32_e32 v190, v190, v50
	v_add_f32_e32 v191, v191, v51
	v_cvt_pk_bf16_f32 v49, v50, v51
	v_exp_f32_e32 v62, v62
	v_exp_f32_e32 v63, v63
	s_waitcnt lgkmcnt(7)
	v_mfma_f32_32x32x16_bf16 v[0:15], v[222:225], v[32:35], v[0:15]
	ds_read_b128 v[222:225], v186
	v_add_f32_e32 v192, v192, v52
	v_add_f32_e32 v193, v193, v53
	v_cvt_pk_bf16_f32 v50, v52, v53
	v_exp_f32_e32 v64, v64
	v_exp_f32_e32 v65, v65
	s_waitcnt lgkmcnt(7)
	v_mfma_f32_32x32x16_bf16 v[16:31], v[226:229], v[32:35], v[16:31]
	ds_read_b128 v[226:229], v186 offset:4608
	v_add_f32_e32 v194, v194, v54
	v_add_f32_e32 v195, v195, v55
	v_cvt_pk_bf16_f32 v51, v54, v55
	v_exp_f32_e32 v66, v66
	v_exp_f32_e32 v67, v67
	s_waitcnt lgkmcnt(7)
	v_mfma_f32_32x32x16_bf16 v[0:15], v[230:233], v[36:39], v[0:15]
	ds_read_b128 v[230:233], v186 offset:32
	v_add_f32_e32 v196, v196, v56
	v_add_f32_e32 v197, v197, v57
	v_cvt_pk_bf16_f32 v52, v56, v57
	v_exp_f32_e32 v68, v68
	v_exp_f32_e32 v69, v69
	s_waitcnt vmcnt(3)
	ds_write_b128 v168, v[80:83] offset:9216
	s_waitcnt vmcnt(2)
	ds_write_b128 v168, v[84:87] offset:18432
	s_waitcnt lgkmcnt(9)
	v_mfma_f32_32x32x16_bf16 v[16:31], v[234:237], v[36:39], v[16:31]
	ds_read_b128 v[234:237], v186 offset:4640
	v_add_f32_e32 v198, v198, v58
	v_add_f32_e32 v199, v199, v59
	v_cvt_pk_bf16_f32 v53, v58, v59
	v_exp_f32_e32 v70, v70
	v_exp_f32_e32 v71, v71
	s_waitcnt vmcnt(1)
	ds_write2_b64 v169, v[88:89], v[90:91] offset1:2
	s_waitcnt vmcnt(0)
	ds_write2_b64 v170, v[92:93], v[94:95] offset0:128 offset1:130
	s_waitcnt lgkmcnt(11)
	v_mfma_f32_32x32x16_bf16 v[0:15], v[138:141], v[48:51], v[0:15]
	ds_read_b128 v[138:141], v186 offset:64
	v_add_f32_e32 v200, v200, v60
	v_add_f32_e32 v201, v201, v61
	v_cvt_pk_bf16_f32 v54, v60, v61
	v_exp_f32_e32 v72, v72
	v_exp_f32_e32 v73, v73
	s_mov_b32 s98, 0xd918000
	v_lshl_add_u64 v[146:147], v[120:121], 0, s[98:99]
	global_load_dwordx4 v[112:115], v[146:147], off offset:2304
	s_mov_b32 s98, 0xd940000
	s_waitcnt lgkmcnt(11)
	v_mfma_f32_32x32x16_bf16 v[16:31], v[142:145], v[48:51], v[16:31]
	ds_read_b128 v[142:145], v186 offset:4672
	v_add_f32_e32 v202, v202, v62
	v_add_f32_e32 v203, v203, v63
	v_cvt_pk_bf16_f32 v55, v62, v63
	v_exp_f32_e32 v74, v74
	v_exp_f32_e32 v75, v75
	v_lshl_add_u64 v[146:147], v[120:121], 0, s[98:99]
	global_load_dwordx4 v[116:119], v[146:147], off offset:2304
	s_mov_b32 s98, 0x17830000
	v_lshl_add_u64 v[146:147], v[124:125], 0, s[98:99]
	s_waitcnt lgkmcnt(11)
	v_mfma_f32_32x32x16_bf16 v[0:15], v[162:165], v[52:55], v[0:15]
	ds_read_b128 v[162:165], v186 offset:96
	v_exp_f32_e32 v76, v76
	v_exp_f32_e32 v77, v77
	global_load_dwordx4 v[120:123], v[146:147], off
	s_mov_b32 s98, 0x17838000
	v_lshl_add_u64 v[146:147], v[124:125], 0, s[98:99]
	global_load_dwordx4 v[124:127], v[146:147], off
	s_waitcnt lgkmcnt(11)
	v_mfma_f32_32x32x16_bf16 v[16:31], v[132:135], v[52:55], v[16:31]
	ds_read_b128 v[132:135], v186 offset:4704
	v_exp_f32_e32 v78, v78
	v_exp_f32_e32 v79, v79
	s_add_i32 s7, s84, 4
	s_cmp_ge_u32 s6, s82
	s_cbranch_scc1 .Lattn_tail
	s_waitcnt lgkmcnt(11)
	v_mfma_f32_32x32x16_bf16 v[32:47], v[222:225], v[96:99], 0
	ds_read_b128 v[222:225], v186 offset:64512
	v_add_f32_e32 v188, v188, v64
	v_add_f32_e32 v189, v189, v65
	v_cvt_pk_bf16_f32 v64, v64, v65
	v_add_f32_e32 v190, v190, v66
	v_add_f32_e32 v191, v191, v67
	v_cvt_pk_bf16_f32 v65, v66, v67
	v_exp_f32_e32 v206, v206
	v_exp_f32_e32 v207, v207
	s_waitcnt lgkmcnt(11)
	v_mfma_f32_32x32x16_bf16 v[48:63], v[226:229], v[96:99], 0
	ds_read_b128 v[226:229], v187 offset:32256
	v_add_f32_e32 v192, v192, v68
	v_add_f32_e32 v193, v193, v69
	v_cvt_pk_bf16_f32 v66, v68, v69
	v_exp_f32_e32 v208, v208
	v_exp_f32_e32 v209, v209
	s_waitcnt lgkmcnt(11)
	v_mfma_f32_32x32x16_bf16 v[32:47], v[230:233], v[100:103], v[32:47]
	ds_read_b128 v[230:233], v186 offset:64544
	v_add_f32_e32 v194, v194, v70
	v_add_f32_e32 v195, v195, v71
	v_cvt_pk_bf16_f32 v67, v70, v71
	v_exp_f32_e32 v210, v210
	v_exp_f32_e32 v211, v211
	s_waitcnt lgkmcnt(9)
	v_mfma_f32_32x32x16_bf16 v[48:63], v[234:237], v[100:103], v[48:63]
	ds_read_b128 v[234:237], v187 offset:32288
	v_add_f32_e32 v196, v196, v72
	v_add_f32_e32 v197, v197, v73
	v_cvt_pk_bf16_f32 v68, v72, v73
	v_exp_f32_e32 v212, v212
	v_exp_f32_e32 v213, v213
	s_waitcnt lgkmcnt(7)
	v_mfma_f32_32x32x16_bf16 v[32:47], v[138:141], v[104:107], v[32:47]
	ds_read_b128 v[138:141], v186 offset:64576
	v_add_f32_e32 v198, v198, v74
	v_add_f32_e32 v199, v199, v75
	v_cvt_pk_bf16_f32 v69, v74, v75
	v_exp_f32_e32 v214, v214
	v_exp_f32_e32 v215, v215
	s_waitcnt lgkmcnt(7)
	v_mfma_f32_32x32x16_bf16 v[48:63], v[142:145], v[104:107], v[48:63]
	ds_read_b128 v[142:145], v187 offset:32320
	v_add_f32_e32 v200, v200, v76
	v_add_f32_e32 v201, v201, v77
	v_cvt_pk_bf16_f32 v70, v76, v77
	v_exp_f32_e32 v216, v216
	v_exp_f32_e32 v217, v217
	s_waitcnt lgkmcnt(7)
	v_mfma_f32_32x32x16_bf16 v[32:47], v[162:165], v[108:111], v[32:47]
	ds_read_b128 v[162:165], v186 offset:64608
	v_add_f32_e32 v202, v202, v78
	v_add_f32_e32 v203, v203, v79
	v_cvt_pk_bf16_f32 v71, v78, v79
	v_exp_f32_e32 v218, v218
	v_exp_f32_e32 v219, v219
	s_waitcnt lgkmcnt(7)
	v_mfma_f32_32x32x16_bf16 v[48:63], v[132:135], v[108:111], v[48:63]
	ds_read_b128 v[132:135], v187 offset:32352
	v_add_f32_e32 v188, v188, v206
	v_add_f32_e32 v189, v189, v207
	v_cvt_pk_bf16_f32 v206, v206, v207
	v_add_f32_e32 v190, v190, v208
	v_add_f32_e32 v191, v191, v209
	v_cvt_pk_bf16_f32 v207, v208, v209
	v_exp_f32_e32 v220, v220
	v_exp_f32_e32 v221, v221
	s_waitcnt lgkmcnt(7)
	v_mfma_f32_32x32x16_bf16 v[0:15], v[222:225], v[64:67], v[0:15]
	v_add_f32_e32 v192, v192, v210
	v_add_f32_e32 v193, v193, v211
	v_cvt_pk_bf16_f32 v208, v210, v211
	v_exp_f32_e32 v32, v32
	v_exp_f32_e32 v33, v33
	s_waitcnt lgkmcnt(6)
	v_mfma_f32_32x32x16_bf16 v[16:31], v[226:229], v[64:67], v[16:31]
	v_add_f32_e32 v194, v194, v212
	v_add_f32_e32 v195, v195, v213
	v_cvt_pk_bf16_f32 v209, v212, v213
	v_exp_f32_e32 v34, v34
	v_exp_f32_e32 v35, v35
	s_waitcnt lgkmcnt(5)
	v_mfma_f32_32x32x16_bf16 v[0:15], v[230:233], v[68:71], v[0:15]
	v_add_f32_e32 v196, v196, v214
	v_add_f32_e32 v197, v197, v215
	v_cvt_pk_bf16_f32 v210, v214, v215
	v_exp_f32_e32 v36, v36
	v_exp_f32_e32 v37, v37
	s_waitcnt lgkmcnt(4)
	v_mfma_f32_32x32x16_bf16 v[16:31], v[234:237], v[68:71], v[16:31]
	s_waitcnt lgkmcnt(0)
	s_barrier
	ds_read_b128 v[222:225], v186 offset:9216
	ds_read_b128 v[226:229], v186 offset:13824
	ds_read_b128 v[230:233], v186 offset:9248
	ds_read_b128 v[234:237], v186 offset:13856
	v_add_f32_e32 v198, v198, v216
	v_add_f32_e32 v199, v199, v217
	v_cvt_pk_bf16_f32 v211, v216, v217
	v_exp_f32_e32 v38, v38
	v_exp_f32_e32 v39, v39
	v_mfma_f32_32x32x16_bf16 v[0:15], v[138:141], v[206:209], v[0:15]
	ds_read_b128 v[138:141], v186 offset:9280
	v_add_f32_e32 v200, v200, v218
	v_add_f32_e32 v201, v201, v219
	v_cvt_pk_bf16_f32 v212, v218, v219
	v_exp_f32_e32 v40, v40
	v_exp_f32_e32 v41, v41
	v_mfma_f32_32x32x16_bf16 v[16:31], v[142:145], v[206:209], v[16:31]
	ds_read_b128 v[142:145], v186 offset:13888
	v_add_f32_e32 v202, v202, v220
	v_add_f32_e32 v203, v203, v221
	v_cvt_pk_bf16_f32 v213, v220, v221
	v_exp_f32_e32 v42, v42
	v_exp_f32_e32 v43, v43
	v_mfma_f32_32x32x16_bf16 v[0:15], v[162:165], v[210:213], v[0:15]
	ds_read_b128 v[162:165], v186 offset:9312
	v_exp_f32_e32 v44, v44
	v_exp_f32_e32 v45, v45
	v_mfma_f32_32x32x16_bf16 v[16:31], v[132:135], v[210:213], v[16:31]
	ds_read_b128 v[132:135], v186 offset:13920
	v_exp_f32_e32 v46, v46
	v_exp_f32_e32 v47, v47
	v_lshl_add_u64 v[158:159], v[158:159], 0, s[26:27]
	v_lshl_add_u64 v[160:161], v[160:161], 0, s[28:29]
	s_branch .Lattn_main
.Lattn_tail:
	s_waitcnt lgkmcnt(11)
	v_mfma_f32_32x32x16_bf16 v[32:47], v[222:225], v[96:99], 0
	ds_read_b128 v[222:225], v186 offset:64512
	v_add_f32_e32 v188, v188, v64
	v_add_f32_e32 v189, v189, v65
	v_cvt_pk_bf16_f32 v64, v64, v65
	v_add_f32_e32 v190, v190, v66
	v_add_f32_e32 v191, v191, v67
	v_cvt_pk_bf16_f32 v65, v66, v67
	v_exp_f32_e32 v206, v206
	v_exp_f32_e32 v207, v207
	s_waitcnt lgkmcnt(11)
	v_mfma_f32_32x32x16_bf16 v[48:63], v[226:229], v[96:99], 0
	ds_read_b128 v[226:229], v187 offset:32256
	v_add_f32_e32 v192, v192, v68
	v_add_f32_e32 v193, v193, v69
	v_cvt_pk_bf16_f32 v66, v68, v69
	v_exp_f32_e32 v208, v208
	v_exp_f32_e32 v209, v209
	s_waitcnt lgkmcnt(11)
	v_mfma_f32_32x32x16_bf16 v[32:47], v[230:233], v[100:103], v[32:47]
	ds_read_b128 v[230:233], v186 offset:64544
	v_add_f32_e32 v194, v194, v70
	v_add_f32_e32 v195, v195, v71
	v_cvt_pk_bf16_f32 v67, v70, v71
	v_exp_f32_e32 v210, v210
	v_exp_f32_e32 v211, v211
	s_waitcnt lgkmcnt(9)
	v_mfma_f32_32x32x16_bf16 v[48:63], v[234:237], v[100:103], v[48:63]
	ds_read_b128 v[234:237], v187 offset:32288
	v_add_f32_e32 v196, v196, v72
	v_add_f32_e32 v197, v197, v73
	v_cvt_pk_bf16_f32 v68, v72, v73
	v_exp_f32_e32 v212, v212
	v_exp_f32_e32 v213, v213
	s_waitcnt lgkmcnt(7)
	v_mfma_f32_32x32x16_bf16 v[32:47], v[138:141], v[104:107], v[32:47]
	ds_read_b128 v[138:141], v186 offset:64576
	v_add_f32_e32 v198, v198, v74
	v_add_f32_e32 v199, v199, v75
	v_cvt_pk_bf16_f32 v69, v74, v75
	v_exp_f32_e32 v214, v214
	v_exp_f32_e32 v215, v215
	s_waitcnt lgkmcnt(7)
	v_mfma_f32_32x32x16_bf16 v[48:63], v[142:145], v[104:107], v[48:63]
	ds_read_b128 v[142:145], v187 offset:32320
	v_add_f32_e32 v200, v200, v76
	v_add_f32_e32 v201, v201, v77
	v_cvt_pk_bf16_f32 v70, v76, v77
	v_exp_f32_e32 v216, v216
	v_exp_f32_e32 v217, v217
	s_waitcnt lgkmcnt(7)
	v_mfma_f32_32x32x16_bf16 v[32:47], v[162:165], v[108:111], v[32:47]
	ds_read_b128 v[162:165], v186 offset:64608
	v_add_f32_e32 v202, v202, v78
	v_add_f32_e32 v203, v203, v79
	v_cvt_pk_bf16_f32 v71, v78, v79
	v_exp_f32_e32 v218, v218
	v_exp_f32_e32 v219, v219
	s_waitcnt lgkmcnt(7)
	v_mfma_f32_32x32x16_bf16 v[48:63], v[132:135], v[108:111], v[48:63]
	ds_read_b128 v[132:135], v187 offset:32352
	v_add_f32_e32 v188, v188, v206
	v_add_f32_e32 v189, v189, v207
	v_cvt_pk_bf16_f32 v206, v206, v207
	v_add_f32_e32 v190, v190, v208
	v_add_f32_e32 v191, v191, v209
	v_cvt_pk_bf16_f32 v207, v208, v209
	v_exp_f32_e32 v220, v220
	v_exp_f32_e32 v221, v221
	s_waitcnt lgkmcnt(7)
	v_mfma_f32_32x32x16_bf16 v[0:15], v[222:225], v[64:67], v[0:15]
	v_add_f32_e32 v192, v192, v210
	v_add_f32_e32 v193, v193, v211
	v_cvt_pk_bf16_f32 v208, v210, v211
	s_nop 0
	s_nop 0
	s_waitcnt lgkmcnt(6)
	v_mfma_f32_32x32x16_bf16 v[16:31], v[226:229], v[64:67], v[16:31]
	v_add_f32_e32 v194, v194, v212
	v_add_f32_e32 v195, v195, v213
	v_cvt_pk_bf16_f32 v209, v212, v213
	s_nop 0
	s_nop 0
	s_waitcnt lgkmcnt(5)
	v_mfma_f32_32x32x16_bf16 v[0:15], v[230:233], v[68:71], v[0:15]
	v_add_f32_e32 v196, v196, v214
	v_add_f32_e32 v197, v197, v215
	v_cvt_pk_bf16_f32 v210, v214, v215
	s_nop 0
	s_nop 0
	s_waitcnt lgkmcnt(4)
	v_mfma_f32_32x32x16_bf16 v[16:31], v[234:237], v[68:71], v[16:31]
	s_waitcnt lgkmcnt(0)
	s_barrier
	ds_read_b128 v[222:225], v186 offset:9216
	ds_read_b128 v[226:229], v186 offset:13824
	ds_read_b128 v[230:233], v186 offset:9248
	ds_read_b128 v[234:237], v186 offset:13856
	v_add_f32_e32 v198, v198, v216
	v_add_f32_e32 v199, v199, v217
	v_cvt_pk_bf16_f32 v211, v216, v217
	s_nop 0
	s_nop 0
	v_mfma_f32_32x32x16_bf16 v[0:15], v[138:141], v[206:209], v[0:15]
	ds_read_b128 v[138:141], v186 offset:9280
	v_add_f32_e32 v200, v200, v218
	v_add_f32_e32 v201, v201, v219
	v_cvt_pk_bf16_f32 v212, v218, v219
	s_nop 0
	s_nop 0
	v_mfma_f32_32x32x16_bf16 v[16:31], v[142:145], v[206:209], v[16:31]
	ds_read_b128 v[142:145], v186 offset:13888
	v_add_f32_e32 v202, v202, v220
	v_add_f32_e32 v203, v203, v221
	v_cvt_pk_bf16_f32 v213, v220, v221
	s_nop 0
	s_nop 0
	v_mfma_f32_32x32x16_bf16 v[0:15], v[162:165], v[210:213], v[0:15]
	ds_read_b128 v[162:165], v186 offset:9312
	v_mfma_f32_32x32x16_bf16 v[16:31], v[132:135], v[210:213], v[16:31]
	ds_read_b128 v[132:135], v186 offset:13920
